# speedup vs baseline: 1.0136x; 1.0136x over previous
; #define ATTN_DMA(STAGE) do { unsigned char* sb_ = S0 + (STAGE) * STGB + lane * 16; \
;     _Pragma("unroll") for (int i_ = 0; i_ < NKI; ++i_) { dma16(ksrc[i_], sb_ + (w + 8 * i_) * 1024); ksrc[i_] += kstr[i_]; } \
;     _Pragma("unroll") for (int i_ = 0; i_ < 2; ++i_) { dma16(vsrc[i_], sb_ + KBYTES + (w + 8 * i_) * 1024); vsrc[i_] += 64; } } while (0)
; #define SB_() __builtin_amdgcn_sched_barrier(0)
; __device__ __forceinline__ void attn_exp(f32x16& sa, float mx, float& m_run, float& lsum, f32x16 (&o)[4], bf16x8& pb0, bf16x8& pb1) {
;     ...
;     float pv[16];
; #pragma unroll
;     for (int r = 0; r < 16; ++r) { pv[r] = __builtin_amdgcn_exp2f(sa[r] - m_run); lsum += pv[r]; }
;     u32x4 t0 = {pack2(pv[0], pv[1]), pack2(pv[2], pv[3]), pack2(pv[4], pv[5]), pack2(pv[6], pv[7])};
;     u32x4 t1 = {pack2(pv[8], pv[9]), pack2(pv[10], pv[11]), pack2(pv[12], pv[13]), pack2(pv[14], pv[15])};
;     pb0 = __builtin_bit_cast(bf16x8, t0);
;     pb1 = __builtin_bit_cast(bf16x8, t1);
; template <bool MLA>
; __device__ __forceinline__ void attn_item(unsigned char* smem, const Params& p, int b, int hh, int qt) {
;     ...
;         if (kt + 2 < NKT) { const int st2 = stage >= 1 ? stage - 1 : 2; ATTN_DMA(st2); }
;         bf16x8 ka[4], kb[4], kc[4], vf[8];
; #pragma unroll
;         for (int i = 0; i < 4; ++i) ka[i] = KRD(0, i);
;         SB_();
; #pragma unroll
;         for (int hf = 0; hf < 2; ++hf) {
;             if (hf == 1 && kt == NKT - 1) break;
;             f32x16 sa;
; #pragma unroll
;             for (int r = 0; r < 16; ++r) sa[r] = 0.f;
;             if constexpr (MLA) {
;                 __builtin_amdgcn_s_setprio(1);
; #pragma unroll
;                 for (int i = 0; i < 4; ++i) {
;                     sa = __builtin_amdgcn_mfma_f32_32x32x16_bf16(ka[i], qf[i], sa, 0, 0, 0);
;                     kb[i] = KRD(hf, 4 + i);
;                 }
;                 SB_();
; #pragma unroll
;                 for (int i = 0; i < 4; ++i) {
;                     sa = __builtin_amdgcn_mfma_f32_32x32x16_bf16(kb[i], qf[4 + i], sa, 0, 0, 0);
;                     kc[i] = KRD(hf, 8 + i);
;                 }
;                 SB_();
; #pragma unroll
;                 for (int d = 0; d < 2; ++d) { vf[2 * d] = VRD(hf, d, 0); vf[2 * d + 1] = VRD(hf, d, 1); }
; #pragma unroll
;                 for (int i = 0; i < 4; ++i) sa = __builtin_amdgcn_mfma_f32_32x32x16_bf16(kc[i], qf[8 + i], sa, 0, 0, 0);
.LBB0_866:
	v_sub_f32_e32 v74, v212, v198
	v_sub_f32_e32 v75, v211, v198
	v_sub_f32_e32 v76, v210, v198
	v_sub_f32_e32 v77, v208, v198
	v_sub_f32_e32 v78, v207, v198
	v_sub_f32_e32 v79, v206, v198
	v_sub_f32_e32 v80, v205, v198
	v_sub_f32_e32 v81, v204, v198
	v_sub_f32_e32 v73, v73, v198
	v_sub_f32_e32 v72, v72, v198
	v_sub_f32_e32 v71, v71, v198
	v_sub_f32_e32 v70, v70, v198
	v_sub_f32_e32 v69, v69, v198
	v_sub_f32_e32 v68, v68, v198
	v_sub_f32_e32 v67, v67, v198
	v_sub_f32_e32 v66, v66, v198
	v_exp_f32_e32 v74, v74
	v_exp_f32_e32 v75, v75
	v_exp_f32_e32 v76, v76
	v_exp_f32_e32 v77, v77
	v_exp_f32_e32 v78, v78
	v_exp_f32_e32 v79, v79
	v_exp_f32_e32 v80, v80
	v_exp_f32_e32 v81, v81
	v_exp_f32_e32 v73, v73
	v_exp_f32_e32 v72, v72
	v_exp_f32_e32 v71, v71
	v_exp_f32_e32 v70, v70
	v_exp_f32_e32 v69, v69
	v_exp_f32_e32 v68, v68
	v_exp_f32_e32 v204, v67
	v_exp_f32_e32 v205, v66
	v_add_f32_e32 v66, v201, v74
	v_add_f32_e32 v66, v75, v66
	v_add_f32_e32 v66, v76, v66
	v_add_f32_e32 v66, v77, v66
	v_add_f32_e32 v66, v78, v66
	v_add_f32_e32 v66, v79, v66
	v_add_f32_e32 v66, v80, v66
	v_add_f32_e32 v66, v81, v66
	v_add_f32_e32 v66, v73, v66
	v_add_f32_e32 v66, v72, v66
	v_add_f32_e32 v66, v71, v66
	v_add_f32_e32 v66, v70, v66
	v_add_f32_e32 v66, v69, v66
	v_add_f32_e32 v66, v68, v66
	v_add_f32_e32 v66, v204, v66
	v_add_f32_e32 v201, v205, v66
	v_cvt_pk_bf16_f32 v66, v73, v72
	v_cvt_pk_bf16_f32 v67, v71, v70
	v_cvt_pk_bf16_f32 v68, v69, v68
	v_cvt_pk_bf16_f32 v69, v204, v205
	v_cvt_pk_bf16_f32 v70, v74, v75
	v_cvt_pk_bf16_f32 v71, v76, v77
	v_cvt_pk_bf16_f32 v72, v78, v79
	v_cvt_pk_bf16_f32 v73, v80, v81
	ds_read_b128 v[74:77], v202 offset:36864
	ds_read_b128 v[78:81], v203 offset:36864
	ds_read_b128 v[204:207], v202 offset:32768
	ds_read_b128 v[208:211], v203 offset:32768
	s_setprio 0
	v_mfma_f32_32x32x16_bf16 v[50:65], v[138:141], v[70:73], v[50:65]
	v_mfma_f32_32x32x16_bf16 v[34:49], v[130:133], v[70:73], v[34:49]
	s_waitcnt lgkmcnt(0)
	v_mfma_f32_32x32x16_bf16 v[18:33], v[208:211], v[70:73], v[18:33]
	v_mfma_f32_32x32x16_bf16 v[2:17], v[78:81], v[70:73], v[2:17]
	v_mfma_f32_32x32x16_bf16 v[50:65], v[142:145], v[66:69], v[50:65]
	v_mfma_f32_32x32x16_bf16 v[34:49], v[134:137], v[66:69], v[34:49]
	v_mfma_f32_32x32x16_bf16 v[18:33], v[204:207], v[66:69], v[18:33]
	v_mfma_f32_32x32x16_bf16 v[2:17], v[74:77], v[66:69], v[2:17]
	s_setprio 1
	s_add_i32 s3, s2, 1
	s_cmp_lg_u32 s2, 2
	s_waitcnt vmcnt(5)
	s_cselect_b32 s2, s3, 0
	s_add_u32 s0, s0, 0x80
	s_addc_u32 s1, s1, 0
	v_lshl_add_u64 v[158:159], v[158:159], 0, v[154:155]
	v_lshl_add_u64 v[160:161], v[160:161], 0, v[152:153]
	s_cmpk_eq_i32 s0, 0x1f80
	v_lshl_add_u64 v[162:163], v[162:163], 0, v[0:1]
	s_barrier
	s_cbranch_scc1 .LBB0_871
.LBB0_867:
	s_mul_i32 s3, s2, 0xa000
	s_add_i32 s6, s3, 0xffff6000
	s_cmp_gt_i32 s2, 0
	s_cselect_b32 s6, s6, 0x14000
	v_add_u32_e32 v70, s6, v199
	v_add_u32_e32 v71, 0x2000, v70
	v_readfirstlane_b32 s6, v70
	s_mov_b32 m0, s6
	v_readfirstlane_b32 s6, v71
	v_add_u32_e32 v71, 0x4000, v70
	global_load_lds_dwordx4 v[162:163], off
	s_mov_b32 m0, s6
	v_readfirstlane_b32 s6, v71
	v_add_u32_e32 v71, 0x6000, v70
	global_load_lds_dwordx4 v[160:161], off
	s_mov_b32 m0, s6
	v_readfirstlane_b32 s6, v71
	v_lshl_add_u64 v[68:69], v[156:157], 0, s[0:1]
	global_load_lds_dwordx4 v[158:159], off
	s_mov_b32 m0, s6
	v_lshl_add_u64 v[66:67], v[164:165], 0, s[0:1]
	global_load_lds_dwordx4 v[68:69], off
	v_add_u32_e32 v68, 0x8000, v70
	v_add_u32_e32 v70, s3, v200
	v_readfirstlane_b32 s6, v68
	s_mov_b32 m0, s6
	v_add_u32_e32 v203, v70, v192
	global_load_lds_dwordx4 v[66:67], off
	v_add_u32_e32 v205, v70, v196
	v_add_u32_e32 v204, v70, v193
	ds_read_b128 v[66:69], v203
	ds_read_b128 v[130:133], v204
	v_add_u32_e32 v206, v70, v197
	ds_read_b128 v[134:137], v205
	ds_read_b128 v[138:141], v206
	v_or_b32_e32 v202, s3, v194
	s_setprio 0
	s_waitcnt lgkmcnt(0)
	v_mfma_f32_32x32x16_bf16 v[66:81], v[66:69], v[110:113], 0
	ds_read_b128 v[142:145], v203 offset:128
	v_mfma_f32_32x32x16_bf16 v[66:81], v[130:133], v[106:109], v[66:81]
	ds_read_b128 v[130:133], v204 offset:128
	v_mfma_f32_32x32x16_bf16 v[66:81], v[134:137], v[102:105], v[66:81]
	ds_read_b128 v[134:137], v205 offset:128
	v_mfma_f32_32x32x16_bf16 v[66:81], v[138:141], v[98:101], v[66:81]
	ds_read_b128 v[138:141], v206 offset:128
	ds_read_b128 v[208:211], v203 offset:256
	ds_read_b128 v[212:215], v204 offset:256
	ds_read_b128 v[222:225], v205 offset:256
	ds_read_b128 v[226:229], v206 offset:256
	s_waitcnt lgkmcnt(0)
	v_mfma_f32_32x32x16_bf16 v[66:81], v[142:145], v[94:97], v[66:81]
	v_add_u32_e32 v207, v202, v193
	v_mfma_f32_32x32x16_bf16 v[66:81], v[130:133], v[90:93], v[66:81]
	v_mfma_f32_32x32x16_bf16 v[66:81], v[134:137], v[86:89], v[66:81]
	v_mfma_f32_32x32x16_bf16 v[66:81], v[138:141], v[82:85], v[66:81]
	v_mfma_f32_32x32x16_bf16 v[66:81], v[208:211], v[118:121], v[66:81]
	v_add_u32_e32 v208, v202, v192
	ds_read_b128 v[138:141], v208 offset:24576
	ds_read_b128 v[130:133], v208 offset:28672
	ds_read_b128 v[142:145], v207 offset:24576
	ds_read_b128 v[134:137], v207 offset:28672
	v_mfma_f32_32x32x16_bf16 v[66:81], v[212:215], v[126:129], v[66:81]
	v_mfma_f32_32x32x16_bf16 v[66:81], v[222:225], v[114:117], v[66:81]
	v_mfma_f32_32x32x16_bf16 v[66:81], v[226:229], v[122:125], v[66:81]
	s_setprio 1
	s_nop 10
	v_mul_f32_e32 v217, 0x3dd53b94, v66
	v_mul_f32_e32 v216, 0x3dd53b94, v67
	s_mov_b32 s3, 0xff800000
	v_mul_f32_e32 v215, 0x3dd53b94, v68
	v_mul_f32_e32 v214, 0x3dd53b94, v69
	v_mul_f32_e32 v210, 0x3dd53b94, v73
	v_mul_f32_e32 v73, 0x3dd53b94, v74
	v_max3_f32 v74, v217, s3, v216
	v_mul_f32_e32 v213, 0x3dd53b94, v70
	v_mul_f32_e32 v212, 0x3dd53b94, v71
	v_max3_f32 v74, v74, v215, v214
	v_mul_f32_e32 v211, 0x3dd53b94, v72
	v_max3_f32 v74, v74, v213, v212
	v_mul_f32_e32 v72, 0x3dd53b94, v75
	v_max3_f32 v74, v74, v211, v210
	v_mul_f32_e32 v71, 0x3dd53b94, v76
	v_mul_f32_e32 v70, 0x3dd53b94, v77
	v_max3_f32 v74, v74, v73, v72
	v_mul_f32_e32 v69, 0x3dd53b94, v78
	v_mul_f32_e32 v68, 0x3dd53b94, v79
	v_max3_f32 v74, v74, v71, v70
	v_mul_f32_e32 v67, 0x3dd53b94, v80
	v_mul_f32_e32 v66, 0x3dd53b94, v81
	v_max3_f32 v74, v74, v69, v68
	v_max3_f32 v74, v74, v67, v66
	ds_bpermute_b32 v75, v149, v74
	v_add_f32_e32 v209, 0x41000000, v198
	s_waitcnt lgkmcnt(0)
	v_max_f32_e32 v75, v75, v75
	v_max_f32_e32 v74, v74, v75
	v_cmp_le_f32_e32 vcc, v74, v209
	s_cmp_eq_u64 vcc, exec
	s_cbranch_scc1 .LBB0_869
; __device__ __forceinline__ void attn_exp(f32x16& sa, float mx, float& m_run, float& lsum, f32x16 (&o)[4], bf16x8& pb0, bf16x8& pb1) {
;     if (!__all(mx <= m_run + ATT_THR)) {
;         const float m_new = fmaxf(m_run, mx);
;         const float alpha = __builtin_amdgcn_exp2f(m_run - m_new);
;         m_run = m_new;
;         lsum *= alpha;
; #pragma unroll
;         for (int d = 0; d < 4; ++d)
; #pragma unroll
;             for (int r = 0; r < 16; ++r) o[d][r] *= alpha;
;     }
;     float pv[16];
; #pragma unroll
;     for (int r = 0; r < 16; ++r) { pv[r] = __builtin_amdgcn_exp2f(sa[r] - m_run); lsum += pv[r]; }
;     u32x4 t0 = {pack2(pv[0], pv[1]), pack2(pv[2], pv[3]), pack2(pv[4], pv[5]), pack2(pv[6], pv[7])};
;     u32x4 t1 = {pack2(pv[8], pv[9]), pack2(pv[10], pv[11]), pack2(pv[12], pv[13]), pack2(pv[14], pv[15])};
;     pb0 = __builtin_bit_cast(bf16x8, t0);
;     pb1 = __builtin_bit_cast(bf16x8, t1);
; template <bool MLA>
; __device__ __forceinline__ void attn_item(unsigned char* smem, const Params& p, int b, int hh, int qt) {
;     ...
;                 for (int d = 2; d < 4; ++d) { vf[2 * d] = VRD(hf, d, 0); vf[2 * d + 1] = VRD(hf, d, 1); }
;             }
;             if (hf == 0 && kt != NKT - 1) {
; #pragma unroll
;                 for (int i = 0; i < 4; ++i) ka[i] = KRD(1, i);
;             }
;             __builtin_amdgcn_s_setprio(1);
; #pragma unroll
;             for (int d = 0; d < 4; ++d) {
;                 o[d] = __builtin_amdgcn_mfma_f32_32x32x16_bf16(vf[2 * d], pb0, o[d], 0, 0, 0);
;                 o[d] = __builtin_amdgcn_mfma_f32_32x32x16_bf16(vf[2 * d + 1], pb1, o[d], 0, 0, 0);
;             }
	v_max_f32_e32 v74, v74, v74
	v_max_f32_e32 v75, v198, v198
	v_max_f32_e32 v75, v75, v74
	v_sub_f32_e32 v74, v198, v75
	v_exp_f32_e32 v74, v74
	v_add_f32_e32 v209, 0x41000000, v75
	v_mov_b32_e32 v198, v75
	v_mul_f32_e32 v201, v201, v74
	v_pk_mul_f32 v[64:65], v[64:65], v[74:75] op_sel_hi:[1,0]
	v_pk_mul_f32 v[62:63], v[62:63], v[74:75] op_sel_hi:[1,0]
	v_pk_mul_f32 v[60:61], v[60:61], v[74:75] op_sel_hi:[1,0]
	v_pk_mul_f32 v[58:59], v[58:59], v[74:75] op_sel_hi:[1,0]
	v_pk_mul_f32 v[56:57], v[56:57], v[74:75] op_sel_hi:[1,0]
	v_pk_mul_f32 v[54:55], v[54:55], v[74:75] op_sel_hi:[1,0]
	v_pk_mul_f32 v[52:53], v[52:53], v[74:75] op_sel_hi:[1,0]
	v_pk_mul_f32 v[50:51], v[50:51], v[74:75] op_sel_hi:[1,0]
	v_pk_mul_f32 v[48:49], v[48:49], v[74:75] op_sel_hi:[1,0]
	v_pk_mul_f32 v[46:47], v[46:47], v[74:75] op_sel_hi:[1,0]
	v_pk_mul_f32 v[44:45], v[44:45], v[74:75] op_sel_hi:[1,0]
	v_pk_mul_f32 v[42:43], v[42:43], v[74:75] op_sel_hi:[1,0]
	v_pk_mul_f32 v[40:41], v[40:41], v[74:75] op_sel_hi:[1,0]
	v_pk_mul_f32 v[38:39], v[38:39], v[74:75] op_sel_hi:[1,0]
	v_pk_mul_f32 v[36:37], v[36:37], v[74:75] op_sel_hi:[1,0]
	v_pk_mul_f32 v[34:35], v[34:35], v[74:75] op_sel_hi:[1,0]
	v_pk_mul_f32 v[32:33], v[32:33], v[74:75] op_sel_hi:[1,0]
	v_pk_mul_f32 v[30:31], v[30:31], v[74:75] op_sel_hi:[1,0]
	v_pk_mul_f32 v[28:29], v[28:29], v[74:75] op_sel_hi:[1,0]
	v_pk_mul_f32 v[26:27], v[26:27], v[74:75] op_sel_hi:[1,0]
	v_pk_mul_f32 v[24:25], v[24:25], v[74:75] op_sel_hi:[1,0]
	v_pk_mul_f32 v[22:23], v[22:23], v[74:75] op_sel_hi:[1,0]
	v_pk_mul_f32 v[20:21], v[20:21], v[74:75] op_sel_hi:[1,0]
	v_pk_mul_f32 v[18:19], v[18:19], v[74:75] op_sel_hi:[1,0]
	v_pk_mul_f32 v[16:17], v[16:17], v[74:75] op_sel_hi:[1,0]
	v_pk_mul_f32 v[14:15], v[14:15], v[74:75] op_sel_hi:[1,0]
	v_pk_mul_f32 v[12:13], v[12:13], v[74:75] op_sel_hi:[1,0]
	v_pk_mul_f32 v[10:11], v[10:11], v[74:75] op_sel_hi:[1,0]
	v_pk_mul_f32 v[8:9], v[8:9], v[74:75] op_sel_hi:[1,0]
	v_pk_mul_f32 v[6:7], v[6:7], v[74:75] op_sel_hi:[1,0]
	v_pk_mul_f32 v[4:5], v[4:5], v[74:75] op_sel_hi:[1,0]
	v_pk_mul_f32 v[2:3], v[2:3], v[74:75] op_sel_hi:[1,0]
.LBB0_869:
	v_sub_f32_e32 v74, v217, v198
	v_exp_f32_e32 v222, v74
	v_sub_f32_e32 v74, v216, v198
	v_exp_f32_e32 v223, v74
	v_sub_f32_e32 v74, v215, v198
	v_exp_f32_e32 v224, v74
	v_sub_f32_e32 v74, v214, v198
	v_exp_f32_e32 v225, v74
	v_sub_f32_e32 v74, v213, v198
	v_exp_f32_e32 v226, v74
	v_sub_f32_e32 v74, v212, v198
	v_exp_f32_e32 v227, v74
	v_sub_f32_e32 v74, v211, v198
	v_exp_f32_e32 v228, v74
	v_sub_f32_e32 v74, v210, v198
	v_sub_f32_e32 v73, v73, v198
	v_sub_f32_e32 v72, v72, v198
	v_sub_f32_e32 v71, v71, v198
	v_sub_f32_e32 v70, v70, v198
	v_sub_f32_e32 v69, v69, v198
	v_sub_f32_e32 v68, v68, v198
	v_sub_f32_e32 v67, v67, v198
	v_sub_f32_e32 v66, v66, v198
	v_exp_f32_e32 v229, v74
	v_exp_f32_e32 v230, v73
	v_exp_f32_e32 v231, v72
	v_exp_f32_e32 v232, v71
	v_exp_f32_e32 v233, v70
	v_exp_f32_e32 v234, v69
	v_exp_f32_e32 v235, v68
	v_exp_f32_e32 v236, v67
	v_exp_f32_e32 v237, v66
	v_cvt_pk_bf16_f32 v66, v222, v223
	v_cvt_pk_bf16_f32 v67, v224, v225
	v_cvt_pk_bf16_f32 v68, v226, v227
	v_cvt_pk_bf16_f32 v69, v228, v229
	v_cvt_pk_bf16_f32 v70, v230, v231
	v_cvt_pk_bf16_f32 v71, v232, v233
	v_cvt_pk_bf16_f32 v72, v234, v235
	v_cvt_pk_bf16_f32 v73, v236, v237
	v_add_f32_e32 v201, v201, v222
	v_add_f32_e32 v201, v223, v201
	v_add_f32_e32 v201, v224, v201
	v_add_f32_e32 v201, v225, v201
	v_add_f32_e32 v201, v226, v201
	v_add_f32_e32 v201, v227, v201
	v_add_f32_e32 v201, v228, v201
	v_add_f32_e32 v201, v229, v201
	v_add_f32_e32 v201, v230, v201
	v_add_f32_e32 v201, v231, v201
	v_add_f32_e32 v201, v232, v201
	v_add_f32_e32 v201, v233, v201
	v_add_f32_e32 v201, v234, v201
	v_add_f32_e32 v201, v235, v201
	v_add_f32_e32 v201, v236, v201
	ds_read_b128 v[74:77], v208 offset:32768
	ds_read_b128 v[78:81], v207 offset:32768
	ds_read_b128 v[210:213], v208 offset:36864
	ds_read_b128 v[214:217], v207 offset:36864
	v_add_f32_e32 v201, v237, v201
	ds_read_b128 v[222:225], v203 offset:12288
	ds_read_b128 v[226:229], v204 offset:12288
	ds_read_b128 v[230:233], v205 offset:12288
	ds_read_b128 v[234:237], v206 offset:12288
	s_setprio 0
	v_mfma_f32_32x32x16_bf16 v[50:65], v[138:141], v[66:69], v[50:65]
	v_mfma_f32_32x32x16_bf16 v[34:49], v[130:133], v[66:69], v[34:49]
	s_waitcnt lgkmcnt(0)
; template <bool MLA>
; __device__ __forceinline__ void attn_item(unsigned char* smem, const Params& p, int b, int hh, int qt) {
;     ...
;                 for (int i = 0; i < 4; ++i) {
;                     sa = __builtin_amdgcn_mfma_f32_32x32x16_bf16(ka[i], qf[i], sa, 0, 0, 0);
;                     kb[i] = KRD(hf, 4 + i);
;                 }
;                 SB_();
; #pragma unroll
;                 for (int i = 0; i < 4; ++i) {
;                     sa = __builtin_amdgcn_mfma_f32_32x32x16_bf16(kb[i], qf[4 + i], sa, 0, 0, 0);
;                     kc[i] = KRD(hf, 8 + i);
;                 }
;                 SB_();
; #pragma unroll
;                 for (int d = 0; d < 2; ++d) { vf[2 * d] = VRD(hf, d, 0); vf[2 * d + 1] = VRD(hf, d, 1); }
; #pragma unroll
;                 for (int i = 0; i < 4; ++i) sa = __builtin_amdgcn_mfma_f32_32x32x16_bf16(kc[i], qf[8 + i], sa, 0, 0, 0);
;                 __builtin_amdgcn_s_setprio(0);
;             } else {
; #pragma unroll
;                 for (int i = 0; i < 4; ++i) sa = __builtin_amdgcn_mfma_f32_32x32x16_bf16(ka[i], qf[i], sa, 0, 0, 0);
;                 SB_();
;                 const float mx = attn_scores<false>(sa, c1, slope2, qpos, q0w, k0 + hf * 32, h5, kt == NKT - 1);
;                 const bool skip = __all(mx < m_run - 40.0f);
;                 if (hf == 0 && kt != NKT - 1) {
; #pragma unroll
;                     for (int i = 0; i < 4; ++i) ka[i] = KRD(1, i);
;                 }
;                 if (!skip) {
; #pragma unroll
;                     for (int d = 0; d < 4; ++d) { vf[2 * d] = VRD(hf, d, 0); vf[2 * d + 1] = VRD(hf, d, 1); }
;                     bf16x8 pb0, pb1;
;                     attn_exp(sa, mx, m_run, lsum, o, pb0, pb1);
;                     SB_();
; #pragma unroll
;                     for (int d = 0; d < 4; ++d) {
;                         o[d] = __builtin_amdgcn_mfma_f32_32x32x16_bf16(vf[2 * d], pb0, o[d], 0, 0, 0);
;                         o[d] = __builtin_amdgcn_mfma_f32_32x32x16_bf16(vf[2 * d + 1], pb1, o[d], 0, 0, 0);
;                     }
;                 }
;                 SB_();
;                 continue;
;             }
;             SB_();
;             bf16x8 pb0, pb1;
;             attn_softmax<MLA>(sa, c1, slope2, qpos, q0w, k0 + hf * 32, h5, kt == NKT - 1, m_run, lsum, o, pb0, pb1);
;             SB_();
;             if constexpr (MLA) {
; #pragma unroll
	v_mfma_f32_32x32x16_bf16 v[18:33], v[74:77], v[66:69], v[18:33]
	v_mfma_f32_32x32x16_bf16 v[2:17], v[210:213], v[66:69], v[2:17]
	v_mfma_f32_32x32x16_bf16 v[50:65], v[142:145], v[70:73], v[50:65]
	v_mfma_f32_32x32x16_bf16 v[34:49], v[134:137], v[70:73], v[34:49]
	v_mfma_f32_32x32x16_bf16 v[18:33], v[78:81], v[70:73], v[18:33]
	v_mfma_f32_32x32x16_bf16 v[2:17], v[214:217], v[70:73], v[2:17]
	s_setprio 1
	s_setprio 0
	v_mfma_f32_32x32x16_bf16 v[66:81], v[222:225], v[110:113], 0
	ds_read_b128 v[130:133], v203 offset:12416
	ds_read_b128 v[134:137], v204 offset:12416
	ds_read_b128 v[138:141], v205 offset:12416
	ds_read_b128 v[142:145], v206 offset:12416
	v_mfma_f32_32x32x16_bf16 v[66:81], v[226:229], v[106:109], v[66:81]
	v_mfma_f32_32x32x16_bf16 v[66:81], v[230:233], v[102:105], v[66:81]
	v_mfma_f32_32x32x16_bf16 v[66:81], v[234:237], v[98:101], v[66:81]
	ds_read_b128 v[210:213], v203 offset:12544
	ds_read_b128 v[214:217], v204 offset:12544
	ds_read_b128 v[222:225], v205 offset:12544
	ds_read_b128 v[204:207], v206 offset:12544
	s_waitcnt lgkmcnt(0)
	v_mfma_f32_32x32x16_bf16 v[66:81], v[130:133], v[94:97], v[66:81]
	v_add_u32_e32 v203, v202, v196
	v_add_u32_e32 v202, v202, v197
	v_mfma_f32_32x32x16_bf16 v[66:81], v[134:137], v[90:93], v[66:81]
	v_mfma_f32_32x32x16_bf16 v[66:81], v[138:141], v[86:89], v[66:81]
	v_mfma_f32_32x32x16_bf16 v[66:81], v[142:145], v[82:85], v[66:81]
	ds_read_b128 v[138:141], v203 offset:24576
	ds_read_b128 v[130:133], v203 offset:28672
	ds_read_b128 v[142:145], v202 offset:24576
	ds_read_b128 v[134:137], v202 offset:28672
	v_mfma_f32_32x32x16_bf16 v[66:81], v[210:213], v[118:121], v[66:81]
	v_mfma_f32_32x32x16_bf16 v[66:81], v[214:217], v[126:129], v[66:81]
	v_mfma_f32_32x32x16_bf16 v[66:81], v[222:225], v[114:117], v[66:81]
	v_mfma_f32_32x32x16_bf16 v[66:81], v[204:207], v[122:125], v[66:81]
	s_setprio 1
	s_nop 10
	v_mul_f32_e32 v212, 0x3dd53b94, v66
	v_mul_f32_e32 v211, 0x3dd53b94, v67
	v_mul_f32_e32 v210, 0x3dd53b94, v68
	v_mul_f32_e32 v208, 0x3dd53b94, v69
	v_mul_f32_e32 v204, 0x3dd53b94, v73
	v_mul_f32_e32 v73, 0x3dd53b94, v74
	v_max3_f32 v74, v212, s3, v211
	v_mul_f32_e32 v207, 0x3dd53b94, v70
	v_mul_f32_e32 v206, 0x3dd53b94, v71
	v_max3_f32 v74, v74, v210, v208
	v_mul_f32_e32 v205, 0x3dd53b94, v72
	v_max3_f32 v74, v74, v207, v206
	v_mul_f32_e32 v72, 0x3dd53b94, v75
	v_max3_f32 v74, v74, v205, v204
	v_mul_f32_e32 v71, 0x3dd53b94, v76
	v_mul_f32_e32 v70, 0x3dd53b94, v77
	v_max3_f32 v74, v74, v73, v72
	v_mul_f32_e32 v69, 0x3dd53b94, v78
	v_mul_f32_e32 v68, 0x3dd53b94, v79
	v_max3_f32 v74, v74, v71, v70
	v_mul_f32_e32 v67, 0x3dd53b94, v80
	v_mul_f32_e32 v66, 0x3dd53b94, v81
	v_max3_f32 v74, v74, v69, v68
	v_max3_f32 v74, v74, v67, v66
	ds_bpermute_b32 v75, v149, v74
	s_waitcnt lgkmcnt(0)
	v_max_f32_e32 v75, v75, v75
	v_max_f32_e32 v74, v74, v75
	v_cmp_le_f32_e32 vcc, v74, v209
	s_cmp_eq_u64 vcc, exec
	s_cbranch_scc1 .LBB0_866
	v_max_f32_e32 v74, v74, v74
	v_max_f32_e32 v75, v198, v198
	v_max_f32_e32 v75, v75, v74
	v_sub_f32_e32 v74, v198, v75
	v_exp_f32_e32 v74, v74
	v_mov_b32_e32 v198, v75
	v_mul_f32_e32 v201, v201, v74
	v_pk_mul_f32 v[64:65], v[64:65], v[74:75] op_sel_hi:[1,0]
	v_pk_mul_f32 v[62:63], v[62:63], v[74:75] op_sel_hi:[1,0]
	v_pk_mul_f32 v[60:61], v[60:61], v[74:75] op_sel_hi:[1,0]
	v_pk_mul_f32 v[58:59], v[58:59], v[74:75] op_sel_hi:[1,0]
	v_pk_mul_f32 v[56:57], v[56:57], v[74:75] op_sel_hi:[1,0]
	v_pk_mul_f32 v[54:55], v[54:55], v[74:75] op_sel_hi:[1,0]
	v_pk_mul_f32 v[52:53], v[52:53], v[74:75] op_sel_hi:[1,0]
	v_pk_mul_f32 v[50:51], v[50:51], v[74:75] op_sel_hi:[1,0]
	v_pk_mul_f32 v[48:49], v[48:49], v[74:75] op_sel_hi:[1,0]
	v_pk_mul_f32 v[46:47], v[46:47], v[74:75] op_sel_hi:[1,0]
	v_pk_mul_f32 v[44:45], v[44:45], v[74:75] op_sel_hi:[1,0]
	v_pk_mul_f32 v[42:43], v[42:43], v[74:75] op_sel_hi:[1,0]
	v_pk_mul_f32 v[40:41], v[40:41], v[74:75] op_sel_hi:[1,0]
	v_pk_mul_f32 v[38:39], v[38:39], v[74:75] op_sel_hi:[1,0]
	v_pk_mul_f32 v[36:37], v[36:37], v[74:75] op_sel_hi:[1,0]
	v_pk_mul_f32 v[34:35], v[34:35], v[74:75] op_sel_hi:[1,0]
	v_pk_mul_f32 v[32:33], v[32:33], v[74:75] op_sel_hi:[1,0]
	v_pk_mul_f32 v[30:31], v[30:31], v[74:75] op_sel_hi:[1,0]
	v_pk_mul_f32 v[28:29], v[28:29], v[74:75] op_sel_hi:[1,0]
	v_pk_mul_f32 v[26:27], v[26:27], v[74:75] op_sel_hi:[1,0]
	v_pk_mul_f32 v[24:25], v[24:25], v[74:75] op_sel_hi:[1,0]
	v_pk_mul_f32 v[22:23], v[22:23], v[74:75] op_sel_hi:[1,0]
	v_pk_mul_f32 v[20:21], v[20:21], v[74:75] op_sel_hi:[1,0]
	v_pk_mul_f32 v[18:19], v[18:19], v[74:75] op_sel_hi:[1,0]
	v_pk_mul_f32 v[16:17], v[16:17], v[74:75] op_sel_hi:[1,0]
	v_pk_mul_f32 v[14:15], v[14:15], v[74:75] op_sel_hi:[1,0]
	v_pk_mul_f32 v[12:13], v[12:13], v[74:75] op_sel_hi:[1,0]
	v_pk_mul_f32 v[10:11], v[10:11], v[74:75] op_sel_hi:[1,0]
	v_pk_mul_f32 v[8:9], v[8:9], v[74:75] op_sel_hi:[1,0]
	v_pk_mul_f32 v[6:7], v[6:7], v[74:75] op_sel_hi:[1,0]
	v_pk_mul_f32 v[4:5], v[4:5], v[74:75] op_sel_hi:[1,0]
	v_pk_mul_f32 v[2:3], v[2:3], v[74:75] op_sel_hi:[1,0]
	s_branch .LBB0_866
